# code placement: .p2align 6 in front of the 16 GEMM K-loop heads and the 4 attention tile-loop heads
# baseline (speedup 1.0000x reference)
.LBB0_288:
	s_ashr_i32 s13, s12, 31
	s_lshl_b64 s[16:17], s[12:13], 19
	s_add_u32 s16, s36, s16
	s_addc_u32 s17, s37, s17
	s_and_b64 s[18:19], s[0:1], exec
	s_cselect_b32 s13, s17, s27
	s_cselect_b32 s50, s16, s26
	s_ashr_i32 s15, s14, 31
	s_lshl_b64 s[18:19], s[14:15], 19
	s_add_u32 s18, s30, s18
	s_addc_u32 s19, s31, s19
	s_and_b64 s[28:29], s[0:1], exec
	s_cselect_b32 s15, s19, s25
	s_cselect_b32 s51, s18, s24
	s_add_u32 s52, s24, 0x10000
	s_addc_u32 s53, s25, 0
	s_add_u32 s24, s26, 0x40080
	v_mov_b32_e32 v0, 0
	s_addc_u32 s25, s27, 0
	s_mov_b32 s54, -2
	v_mov_b32_e32 v1, v0
	v_mov_b32_e32 v2, v0
	v_mov_b32_e32 v3, v0
	v_mov_b32_e32 v8, v0
	v_mov_b32_e32 v9, v0
	v_mov_b32_e32 v10, v0
	v_mov_b32_e32 v11, v0
	v_mov_b32_e32 v16, v0
	v_mov_b32_e32 v17, v0
	v_mov_b32_e32 v18, v0
	v_mov_b32_e32 v19, v0
	v_mov_b32_e32 v24, v0
	v_mov_b32_e32 v25, v0
	v_mov_b32_e32 v26, v0
	v_mov_b32_e32 v27, v0
	v_mov_b32_e32 v32, v0
	v_mov_b32_e32 v33, v0
	v_mov_b32_e32 v34, v0
	v_mov_b32_e32 v35, v0
	v_mov_b32_e32 v40, v0
	v_mov_b32_e32 v41, v0
	v_mov_b32_e32 v42, v0
	v_mov_b32_e32 v43, v0
	v_mov_b32_e32 v48, v0
	v_mov_b32_e32 v49, v0
	v_mov_b32_e32 v50, v0
	v_mov_b32_e32 v51, v0
	v_mov_b32_e32 v56, v0
	v_mov_b32_e32 v57, v0
	v_mov_b32_e32 v58, v0
	v_mov_b32_e32 v59, v0
	v_mov_b32_e32 v4, v0
	v_mov_b32_e32 v5, v0
	v_mov_b32_e32 v6, v0
	v_mov_b32_e32 v7, v0
	v_mov_b32_e32 v12, v0
	v_mov_b32_e32 v13, v0
	v_mov_b32_e32 v14, v0
	v_mov_b32_e32 v15, v0
	v_mov_b32_e32 v20, v0
	v_mov_b32_e32 v21, v0
	v_mov_b32_e32 v22, v0
	v_mov_b32_e32 v23, v0
	v_mov_b32_e32 v28, v0
	v_mov_b32_e32 v29, v0
	v_mov_b32_e32 v30, v0
	v_mov_b32_e32 v31, v0
	v_mov_b32_e32 v36, v0
	v_mov_b32_e32 v37, v0
	v_mov_b32_e32 v38, v0
	v_mov_b32_e32 v39, v0
	v_mov_b32_e32 v44, v0
	v_mov_b32_e32 v45, v0
	v_mov_b32_e32 v46, v0
	v_mov_b32_e32 v47, v0
	v_mov_b32_e32 v52, v0
	v_mov_b32_e32 v53, v0
	v_mov_b32_e32 v54, v0
	v_mov_b32_e32 v55, v0
	v_mov_b32_e32 v60, v0
	v_mov_b32_e32 v61, v0
	v_mov_b32_e32 v62, v0
	v_mov_b32_e32 v63, v0
	v_mov_b32_e32 v64, v0
	v_mov_b32_e32 v65, v0
	v_mov_b32_e32 v66, v0
	v_mov_b32_e32 v67, v0
	v_mov_b32_e32 v72, v0
	v_mov_b32_e32 v73, v0
	v_mov_b32_e32 v74, v0
	v_mov_b32_e32 v75, v0
	v_mov_b32_e32 v80, v0
	v_mov_b32_e32 v81, v0
	v_mov_b32_e32 v82, v0
	v_mov_b32_e32 v83, v0
	v_mov_b32_e32 v88, v0
	v_mov_b32_e32 v89, v0
	v_mov_b32_e32 v90, v0
	v_mov_b32_e32 v91, v0
	v_mov_b32_e32 v96, v0
	v_mov_b32_e32 v97, v0
	v_mov_b32_e32 v98, v0
	v_mov_b32_e32 v99, v0
	v_mov_b32_e32 v104, v0
	v_mov_b32_e32 v105, v0
	v_mov_b32_e32 v106, v0
	v_mov_b32_e32 v107, v0
	v_mov_b32_e32 v112, v0
	v_mov_b32_e32 v113, v0
	v_mov_b32_e32 v114, v0
	v_mov_b32_e32 v115, v0
	v_mov_b32_e32 v120, v0
	v_mov_b32_e32 v121, v0
	v_mov_b32_e32 v122, v0
	v_mov_b32_e32 v123, v0
	v_mov_b32_e32 v68, v0
	v_mov_b32_e32 v69, v0
	v_mov_b32_e32 v70, v0
	v_mov_b32_e32 v71, v0
	v_mov_b32_e32 v76, v0
	v_mov_b32_e32 v77, v0
	v_mov_b32_e32 v78, v0
	v_mov_b32_e32 v79, v0
	v_mov_b32_e32 v84, v0
	v_mov_b32_e32 v85, v0
	v_mov_b32_e32 v86, v0
	v_mov_b32_e32 v87, v0
	v_mov_b32_e32 v92, v0
	v_mov_b32_e32 v93, v0
	v_mov_b32_e32 v94, v0
	v_mov_b32_e32 v95, v0
	v_mov_b32_e32 v100, v0
	v_mov_b32_e32 v101, v0
	v_mov_b32_e32 v102, v0
	v_mov_b32_e32 v103, v0
	v_mov_b32_e32 v108, v0
	v_mov_b32_e32 v109, v0
	v_mov_b32_e32 v110, v0
	v_mov_b32_e32 v111, v0
	v_mov_b32_e32 v116, v0
	v_mov_b32_e32 v117, v0
	v_mov_b32_e32 v118, v0
	v_mov_b32_e32 v119, v0
	v_mov_b32_e32 v124, v0
	v_mov_b32_e32 v125, v0
	v_mov_b32_e32 v126, v0
	v_mov_b32_e32 v127, v0
	.p2align	6

.LBB0_407:
	s_add_u32 s47, s38, 0x10000
	s_addc_u32 s48, s39, 0
	s_add_u32 s38, s40, 0xc000
	v_mov_b32_e32 v0, 0
	s_addc_u32 s39, s41, 0
	s_mov_b32 s49, -2
	v_mov_b32_e32 v1, v0
	v_mov_b32_e32 v2, v0
	v_mov_b32_e32 v3, v0
	v_mov_b32_e32 v4, v0
	v_mov_b32_e32 v5, v0
	v_mov_b32_e32 v6, v0
	v_mov_b32_e32 v7, v0
	v_mov_b32_e32 v8, v0
	v_mov_b32_e32 v9, v0
	v_mov_b32_e32 v10, v0
	v_mov_b32_e32 v11, v0
	v_mov_b32_e32 v16, v0
	v_mov_b32_e32 v17, v0
	v_mov_b32_e32 v18, v0
	v_mov_b32_e32 v19, v0
	v_mov_b32_e32 v28, v0
	v_mov_b32_e32 v29, v0
	v_mov_b32_e32 v30, v0
	v_mov_b32_e32 v31, v0
	v_mov_b32_e32 v36, v0
	v_mov_b32_e32 v37, v0
	v_mov_b32_e32 v38, v0
	v_mov_b32_e32 v39, v0
	v_mov_b32_e32 v40, v0
	v_mov_b32_e32 v41, v0
	v_mov_b32_e32 v42, v0
	v_mov_b32_e32 v43, v0
	v_mov_b32_e32 v48, v0
	v_mov_b32_e32 v49, v0
	v_mov_b32_e32 v50, v0
	v_mov_b32_e32 v51, v0
	v_mov_b32_e32 v12, v0
	v_mov_b32_e32 v13, v0
	v_mov_b32_e32 v14, v0
	v_mov_b32_e32 v15, v0
	v_mov_b32_e32 v20, v0
	v_mov_b32_e32 v21, v0
	v_mov_b32_e32 v22, v0
	v_mov_b32_e32 v23, v0
	v_mov_b32_e32 v24, v0
	v_mov_b32_e32 v25, v0
	v_mov_b32_e32 v26, v0
	v_mov_b32_e32 v27, v0
	v_mov_b32_e32 v32, v0
	v_mov_b32_e32 v33, v0
	v_mov_b32_e32 v34, v0
	v_mov_b32_e32 v35, v0
	v_mov_b32_e32 v44, v0
	v_mov_b32_e32 v45, v0
	v_mov_b32_e32 v46, v0
	v_mov_b32_e32 v47, v0
	v_mov_b32_e32 v52, v0
	v_mov_b32_e32 v53, v0
	v_mov_b32_e32 v54, v0
	v_mov_b32_e32 v55, v0
	v_mov_b32_e32 v56, v0
	v_mov_b32_e32 v57, v0
	v_mov_b32_e32 v58, v0
	v_mov_b32_e32 v59, v0
	v_mov_b32_e32 v60, v0
	v_mov_b32_e32 v61, v0
	v_mov_b32_e32 v62, v0
	v_mov_b32_e32 v63, v0
	v_mov_b32_e32 v64, v0
	v_mov_b32_e32 v65, v0
	v_mov_b32_e32 v66, v0
	v_mov_b32_e32 v67, v0
	v_mov_b32_e32 v68, v0
	v_mov_b32_e32 v69, v0
	v_mov_b32_e32 v70, v0
	v_mov_b32_e32 v71, v0
	v_mov_b32_e32 v72, v0
	v_mov_b32_e32 v73, v0
	v_mov_b32_e32 v74, v0
	v_mov_b32_e32 v75, v0
	v_mov_b32_e32 v80, v0
	v_mov_b32_e32 v81, v0
	v_mov_b32_e32 v82, v0
	v_mov_b32_e32 v83, v0
	v_mov_b32_e32 v96, v0
	v_mov_b32_e32 v97, v0
	v_mov_b32_e32 v98, v0
	v_mov_b32_e32 v99, v0
	v_mov_b32_e32 v100, v0
	v_mov_b32_e32 v101, v0
	v_mov_b32_e32 v102, v0
	v_mov_b32_e32 v103, v0
	v_mov_b32_e32 v104, v0
	v_mov_b32_e32 v105, v0
	v_mov_b32_e32 v106, v0
	v_mov_b32_e32 v107, v0
	v_mov_b32_e32 v112, v0
	v_mov_b32_e32 v113, v0
	v_mov_b32_e32 v114, v0
	v_mov_b32_e32 v115, v0
	v_mov_b32_e32 v76, v0
	v_mov_b32_e32 v77, v0
	v_mov_b32_e32 v78, v0
	v_mov_b32_e32 v79, v0
	v_mov_b32_e32 v84, v0
	v_mov_b32_e32 v85, v0
	v_mov_b32_e32 v86, v0
	v_mov_b32_e32 v87, v0
	v_mov_b32_e32 v88, v0
	v_mov_b32_e32 v89, v0
	v_mov_b32_e32 v90, v0
	v_mov_b32_e32 v91, v0
	v_mov_b32_e32 v92, v0
	v_mov_b32_e32 v93, v0
	v_mov_b32_e32 v94, v0
	v_mov_b32_e32 v95, v0
	v_mov_b32_e32 v108, v0
	v_mov_b32_e32 v109, v0
	v_mov_b32_e32 v110, v0
	v_mov_b32_e32 v111, v0
	v_mov_b32_e32 v116, v0
	v_mov_b32_e32 v117, v0
	v_mov_b32_e32 v118, v0
	v_mov_b32_e32 v119, v0
	v_mov_b32_e32 v120, v0
	v_mov_b32_e32 v121, v0
	v_mov_b32_e32 v122, v0
	v_mov_b32_e32 v123, v0
	v_mov_b32_e32 v124, v0
	v_mov_b32_e32 v125, v0
	v_mov_b32_e32 v126, v0
	v_mov_b32_e32 v127, v0
	.p2align	6

.LBB0_491:
	s_ashr_i32 s23, s22, 31
	s_lshl_b64 s[26:27], s[22:23], 19
	s_add_u32 s26, s42, s26
	s_addc_u32 s27, s43, s27
	s_and_b64 s[28:29], s[4:5], exec
	s_cselect_b32 s1, s27, s35
	s_cselect_b32 s7, s26, s34
	s_ashr_i32 s25, s24, 31
	s_lshl_b64 s[28:29], s[24:25], 19
	s_add_u32 s28, s44, s28
	s_addc_u32 s29, s45, s29
	s_and_b64 s[36:37], s[4:5], exec
	s_cselect_b32 s10, s29, s31
	s_cselect_b32 s23, s28, s30
	s_add_u32 s25, s30, 0x10000
	s_addc_u32 s38, s31, 0
	s_add_u32 s30, s34, 0x40080
	v_mov_b32_e32 v0, 0
	s_addc_u32 s31, s35, 0
	s_mov_b32 s39, -2
	v_mov_b32_e32 v1, v0
	v_mov_b32_e32 v2, v0
	v_mov_b32_e32 v3, v0
	v_mov_b32_e32 v4, v0
	v_mov_b32_e32 v5, v0
	v_mov_b32_e32 v6, v0
	v_mov_b32_e32 v7, v0
	v_mov_b32_e32 v8, v0
	v_mov_b32_e32 v9, v0
	v_mov_b32_e32 v10, v0
	v_mov_b32_e32 v11, v0
	v_mov_b32_e32 v12, v0
	v_mov_b32_e32 v13, v0
	v_mov_b32_e32 v14, v0
	v_mov_b32_e32 v15, v0
	v_mov_b32_e32 v16, v0
	v_mov_b32_e32 v17, v0
	v_mov_b32_e32 v18, v0
	v_mov_b32_e32 v19, v0
	v_mov_b32_e32 v20, v0
	v_mov_b32_e32 v21, v0
	v_mov_b32_e32 v22, v0
	v_mov_b32_e32 v23, v0
	v_mov_b32_e32 v24, v0
	v_mov_b32_e32 v25, v0
	v_mov_b32_e32 v26, v0
	v_mov_b32_e32 v27, v0
	v_mov_b32_e32 v28, v0
	v_mov_b32_e32 v29, v0
	v_mov_b32_e32 v30, v0
	v_mov_b32_e32 v31, v0
	v_mov_b32_e32 v64, v0
	v_mov_b32_e32 v65, v0
	v_mov_b32_e32 v66, v0
	v_mov_b32_e32 v67, v0
	v_mov_b32_e32 v68, v0
	v_mov_b32_e32 v69, v0
	v_mov_b32_e32 v70, v0
	v_mov_b32_e32 v71, v0
	v_mov_b32_e32 v72, v0
	v_mov_b32_e32 v73, v0
	v_mov_b32_e32 v74, v0
	v_mov_b32_e32 v75, v0
	v_mov_b32_e32 v76, v0
	v_mov_b32_e32 v77, v0
	v_mov_b32_e32 v78, v0
	v_mov_b32_e32 v79, v0
	v_mov_b32_e32 v80, v0
	v_mov_b32_e32 v81, v0
	v_mov_b32_e32 v82, v0
	v_mov_b32_e32 v83, v0
	v_mov_b32_e32 v84, v0
	v_mov_b32_e32 v85, v0
	v_mov_b32_e32 v86, v0
	v_mov_b32_e32 v87, v0
	v_mov_b32_e32 v88, v0
	v_mov_b32_e32 v89, v0
	v_mov_b32_e32 v90, v0
	v_mov_b32_e32 v91, v0
	v_mov_b32_e32 v92, v0
	v_mov_b32_e32 v93, v0
	v_mov_b32_e32 v94, v0
	v_mov_b32_e32 v95, v0
	v_mov_b32_e32 v32, v0
	v_mov_b32_e32 v33, v0
	v_mov_b32_e32 v34, v0
	v_mov_b32_e32 v35, v0
	v_mov_b32_e32 v36, v0
	v_mov_b32_e32 v37, v0
	v_mov_b32_e32 v38, v0
	v_mov_b32_e32 v39, v0
	v_mov_b32_e32 v40, v0
	v_mov_b32_e32 v41, v0
	v_mov_b32_e32 v42, v0
	v_mov_b32_e32 v43, v0
	v_mov_b32_e32 v44, v0
	v_mov_b32_e32 v45, v0
	v_mov_b32_e32 v46, v0
	v_mov_b32_e32 v47, v0
	v_mov_b32_e32 v48, v0
	v_mov_b32_e32 v49, v0
	v_mov_b32_e32 v50, v0
	v_mov_b32_e32 v51, v0
	v_mov_b32_e32 v52, v0
	v_mov_b32_e32 v53, v0
	v_mov_b32_e32 v54, v0
	v_mov_b32_e32 v55, v0
	v_mov_b32_e32 v56, v0
	v_mov_b32_e32 v57, v0
	v_mov_b32_e32 v58, v0
	v_mov_b32_e32 v59, v0
	v_mov_b32_e32 v60, v0
	v_mov_b32_e32 v61, v0
	v_mov_b32_e32 v62, v0
	v_mov_b32_e32 v63, v0
	v_mov_b32_e32 v96, v0
	v_mov_b32_e32 v97, v0
	v_mov_b32_e32 v98, v0
	v_mov_b32_e32 v99, v0
	v_mov_b32_e32 v100, v0
	v_mov_b32_e32 v101, v0
	v_mov_b32_e32 v102, v0
	v_mov_b32_e32 v103, v0
	v_mov_b32_e32 v104, v0
	v_mov_b32_e32 v105, v0
	v_mov_b32_e32 v106, v0
	v_mov_b32_e32 v107, v0
	v_mov_b32_e32 v108, v0
	v_mov_b32_e32 v109, v0
	v_mov_b32_e32 v110, v0
	v_mov_b32_e32 v111, v0
	v_mov_b32_e32 v112, v0
	v_mov_b32_e32 v113, v0
	v_mov_b32_e32 v114, v0
	v_mov_b32_e32 v115, v0
	v_mov_b32_e32 v116, v0
	v_mov_b32_e32 v117, v0
	v_mov_b32_e32 v118, v0
	v_mov_b32_e32 v119, v0
	v_mov_b32_e32 v120, v0
	v_mov_b32_e32 v121, v0
	v_mov_b32_e32 v122, v0
	v_mov_b32_e32 v123, v0
	v_mov_b32_e32 v124, v0
	v_mov_b32_e32 v125, v0
	v_mov_b32_e32 v126, v0
	v_mov_b32_e32 v127, v0
	.p2align	6

.LBB0_957:
	s_and_b64 vcc, exec, s[0:1]
	s_mov_b32 s28, s25
	s_cbranch_vccnz .LBB0_978
	.p2align	6

.LBB0_984:
	s_and_b64 vcc, exec, s[0:1]
	s_mov_b32 s27, s23
	s_cbranch_vccnz .LBB0_943
	.p2align	6

.LBB0_1070:
	s_ashr_i32 s17, s16, 31
	s_lshl_b64 s[20:21], s[16:17], 18
	s_add_u32 s20, s38, s20
	s_addc_u32 s21, s39, s21
	s_and_b64 s[22:23], s[0:1], exec
	s_cselect_b32 s17, s21, s31
	s_cselect_b32 s52, s20, s30
	s_ashr_i32 s19, s18, 31
	s_lshl_b64 s[22:23], s[18:19], 18
	s_add_u32 s22, s40, s22
	s_addc_u32 s23, s41, s23
	s_and_b64 s[34:35], s[0:1], exec
	s_cselect_b32 s19, s23, s29
	s_cselect_b32 s53, s22, s28
	s_add_u32 s54, s28, 0x10000
	s_addc_u32 s55, s29, 0
	s_add_u32 s28, s30, 0x20080
	v_mov_b32_e32 v0, 0
	s_addc_u32 s29, s31, 0
	s_mov_b32 s56, -2
	v_mov_b32_e32 v1, v0
	v_mov_b32_e32 v2, v0
	v_mov_b32_e32 v3, v0
	v_mov_b32_e32 v4, v0
	v_mov_b32_e32 v5, v0
	v_mov_b32_e32 v6, v0
	v_mov_b32_e32 v7, v0
	v_mov_b32_e32 v12, v0
	v_mov_b32_e32 v13, v0
	v_mov_b32_e32 v14, v0
	v_mov_b32_e32 v15, v0
	v_mov_b32_e32 v20, v0
	v_mov_b32_e32 v21, v0
	v_mov_b32_e32 v22, v0
	v_mov_b32_e32 v23, v0
	v_mov_b32_e32 v28, v0
	v_mov_b32_e32 v29, v0
	v_mov_b32_e32 v30, v0
	v_mov_b32_e32 v31, v0
	v_mov_b32_e32 v36, v0
	v_mov_b32_e32 v37, v0
	v_mov_b32_e32 v38, v0
	v_mov_b32_e32 v39, v0
	v_mov_b32_e32 v44, v0
	v_mov_b32_e32 v45, v0
	v_mov_b32_e32 v46, v0
	v_mov_b32_e32 v47, v0
	v_mov_b32_e32 v52, v0
	v_mov_b32_e32 v53, v0
	v_mov_b32_e32 v54, v0
	v_mov_b32_e32 v55, v0
	v_mov_b32_e32 v8, v0
	v_mov_b32_e32 v9, v0
	v_mov_b32_e32 v10, v0
	v_mov_b32_e32 v11, v0
	v_mov_b32_e32 v16, v0
	v_mov_b32_e32 v17, v0
	v_mov_b32_e32 v18, v0
	v_mov_b32_e32 v19, v0
	v_mov_b32_e32 v24, v0
	v_mov_b32_e32 v25, v0
	v_mov_b32_e32 v26, v0
	v_mov_b32_e32 v27, v0
	v_mov_b32_e32 v32, v0
	v_mov_b32_e32 v33, v0
	v_mov_b32_e32 v34, v0
	v_mov_b32_e32 v35, v0
	v_mov_b32_e32 v40, v0
	v_mov_b32_e32 v41, v0
	v_mov_b32_e32 v42, v0
	v_mov_b32_e32 v43, v0
	v_mov_b32_e32 v48, v0
	v_mov_b32_e32 v49, v0
	v_mov_b32_e32 v50, v0
	v_mov_b32_e32 v51, v0
	v_mov_b32_e32 v56, v0
	v_mov_b32_e32 v57, v0
	v_mov_b32_e32 v58, v0
	v_mov_b32_e32 v59, v0
	v_mov_b32_e32 v60, v0
	v_mov_b32_e32 v61, v0
	v_mov_b32_e32 v62, v0
	v_mov_b32_e32 v63, v0
	v_mov_b32_e32 v64, v0
	v_mov_b32_e32 v65, v0
	v_mov_b32_e32 v66, v0
	v_mov_b32_e32 v67, v0
	v_mov_b32_e32 v68, v0
	v_mov_b32_e32 v69, v0
	v_mov_b32_e32 v70, v0
	v_mov_b32_e32 v71, v0
	v_mov_b32_e32 v76, v0
	v_mov_b32_e32 v77, v0
	v_mov_b32_e32 v78, v0
	v_mov_b32_e32 v79, v0
	v_mov_b32_e32 v80, v0
	v_mov_b32_e32 v81, v0
	v_mov_b32_e32 v82, v0
	v_mov_b32_e32 v83, v0
	v_mov_b32_e32 v96, v0
	v_mov_b32_e32 v97, v0
	v_mov_b32_e32 v98, v0
	v_mov_b32_e32 v99, v0
	v_mov_b32_e32 v100, v0
	v_mov_b32_e32 v101, v0
	v_mov_b32_e32 v102, v0
	v_mov_b32_e32 v103, v0
	v_mov_b32_e32 v104, v0
	v_mov_b32_e32 v105, v0
	v_mov_b32_e32 v106, v0
	v_mov_b32_e32 v107, v0
	v_mov_b32_e32 v108, v0
	v_mov_b32_e32 v109, v0
	v_mov_b32_e32 v110, v0
	v_mov_b32_e32 v111, v0
	v_mov_b32_e32 v72, v0
	v_mov_b32_e32 v73, v0
	v_mov_b32_e32 v74, v0
	v_mov_b32_e32 v75, v0
	v_mov_b32_e32 v84, v0
	v_mov_b32_e32 v85, v0
	v_mov_b32_e32 v86, v0
	v_mov_b32_e32 v87, v0
	v_mov_b32_e32 v88, v0
	v_mov_b32_e32 v89, v0
	v_mov_b32_e32 v90, v0
	v_mov_b32_e32 v91, v0
	v_mov_b32_e32 v92, v0
	v_mov_b32_e32 v93, v0
	v_mov_b32_e32 v94, v0
	v_mov_b32_e32 v95, v0
	v_mov_b32_e32 v112, v0
	v_mov_b32_e32 v113, v0
	v_mov_b32_e32 v114, v0
	v_mov_b32_e32 v115, v0
	v_mov_b32_e32 v116, v0
	v_mov_b32_e32 v117, v0
	v_mov_b32_e32 v118, v0
	v_mov_b32_e32 v119, v0
	v_mov_b32_e32 v120, v0
	v_mov_b32_e32 v121, v0
	v_mov_b32_e32 v122, v0
	v_mov_b32_e32 v123, v0
	v_mov_b32_e32 v124, v0
	v_mov_b32_e32 v125, v0
	v_mov_b32_e32 v126, v0
	v_mov_b32_e32 v127, v0
	.p2align	6

.LBB0_1094:
	s_ashr_i32 s15, s14, 31
	s_lshl_b64 s[18:19], s[14:15], 18
	s_add_u32 s18, s35, s18
	s_addc_u32 s19, s37, s19
	s_and_b64 s[20:21], s[0:1], exec
	s_cselect_b32 s15, s19, s29
	s_cselect_b32 s50, s18, s28
	s_ashr_i32 s17, s16, 31
	s_lshl_b64 s[20:21], s[16:17], 18
	s_add_u32 s20, s38, s20
	s_addc_u32 s21, s39, s21
	s_and_b64 s[30:31], s[0:1], exec
	s_cselect_b32 s17, s21, s27
	s_cselect_b32 s51, s20, s26
	s_add_u32 s52, s26, 0x10000
	s_addc_u32 s53, s27, 0
	s_add_u32 s26, s28, 0x20080
	v_mov_b32_e32 v0, 0
	s_addc_u32 s27, s29, 0
	s_mov_b32 s54, -2
	v_mov_b32_e32 v1, v0
	v_mov_b32_e32 v2, v0
	v_mov_b32_e32 v3, v0
	v_mov_b32_e32 v4, v0
	v_mov_b32_e32 v5, v0
	v_mov_b32_e32 v6, v0
	v_mov_b32_e32 v7, v0
	v_mov_b32_e32 v12, v0
	v_mov_b32_e32 v13, v0
	v_mov_b32_e32 v14, v0
	v_mov_b32_e32 v15, v0
	v_mov_b32_e32 v20, v0
	v_mov_b32_e32 v21, v0
	v_mov_b32_e32 v22, v0
	v_mov_b32_e32 v23, v0
	v_mov_b32_e32 v32, v0
	v_mov_b32_e32 v33, v0
	v_mov_b32_e32 v34, v0
	v_mov_b32_e32 v35, v0
	v_mov_b32_e32 v36, v0
	v_mov_b32_e32 v37, v0
	v_mov_b32_e32 v38, v0
	v_mov_b32_e32 v39, v0
	v_mov_b32_e32 v44, v0
	v_mov_b32_e32 v45, v0
	v_mov_b32_e32 v46, v0
	v_mov_b32_e32 v47, v0
	v_mov_b32_e32 v52, v0
	v_mov_b32_e32 v53, v0
	v_mov_b32_e32 v54, v0
	v_mov_b32_e32 v55, v0
	v_mov_b32_e32 v8, v0
	v_mov_b32_e32 v9, v0
	v_mov_b32_e32 v10, v0
	v_mov_b32_e32 v11, v0
	v_mov_b32_e32 v16, v0
	v_mov_b32_e32 v17, v0
	v_mov_b32_e32 v18, v0
	v_mov_b32_e32 v19, v0
	v_mov_b32_e32 v24, v0
	v_mov_b32_e32 v25, v0
	v_mov_b32_e32 v26, v0
	v_mov_b32_e32 v27, v0
	v_mov_b32_e32 v28, v0
	v_mov_b32_e32 v29, v0
	v_mov_b32_e32 v30, v0
	v_mov_b32_e32 v31, v0
	v_mov_b32_e32 v40, v0
	v_mov_b32_e32 v41, v0
	v_mov_b32_e32 v42, v0
	v_mov_b32_e32 v43, v0
	v_mov_b32_e32 v48, v0
	v_mov_b32_e32 v49, v0
	v_mov_b32_e32 v50, v0
	v_mov_b32_e32 v51, v0
	v_mov_b32_e32 v56, v0
	v_mov_b32_e32 v57, v0
	v_mov_b32_e32 v58, v0
	v_mov_b32_e32 v59, v0
	v_mov_b32_e32 v60, v0
	v_mov_b32_e32 v61, v0
	v_mov_b32_e32 v62, v0
	v_mov_b32_e32 v63, v0
	v_mov_b32_e32 v64, v0
	v_mov_b32_e32 v65, v0
	v_mov_b32_e32 v66, v0
	v_mov_b32_e32 v67, v0
	v_mov_b32_e32 v68, v0
	v_mov_b32_e32 v69, v0
	v_mov_b32_e32 v70, v0
	v_mov_b32_e32 v71, v0
	v_mov_b32_e32 v76, v0
	v_mov_b32_e32 v77, v0
	v_mov_b32_e32 v78, v0
	v_mov_b32_e32 v79, v0
	v_mov_b32_e32 v84, v0
	v_mov_b32_e32 v85, v0
	v_mov_b32_e32 v86, v0
	v_mov_b32_e32 v87, v0
	v_mov_b32_e32 v96, v0
	v_mov_b32_e32 v97, v0
	v_mov_b32_e32 v98, v0
	v_mov_b32_e32 v99, v0
	v_mov_b32_e32 v100, v0
	v_mov_b32_e32 v101, v0
	v_mov_b32_e32 v102, v0
	v_mov_b32_e32 v103, v0
	v_mov_b32_e32 v108, v0
	v_mov_b32_e32 v109, v0
	v_mov_b32_e32 v110, v0
	v_mov_b32_e32 v111, v0
	v_mov_b32_e32 v116, v0
	v_mov_b32_e32 v117, v0
	v_mov_b32_e32 v118, v0
	v_mov_b32_e32 v119, v0
	v_mov_b32_e32 v72, v0
	v_mov_b32_e32 v73, v0
	v_mov_b32_e32 v74, v0
	v_mov_b32_e32 v75, v0
	v_mov_b32_e32 v80, v0
	v_mov_b32_e32 v81, v0
	v_mov_b32_e32 v82, v0
	v_mov_b32_e32 v83, v0
	v_mov_b32_e32 v88, v0
	v_mov_b32_e32 v89, v0
	v_mov_b32_e32 v90, v0
	v_mov_b32_e32 v91, v0
	v_mov_b32_e32 v92, v0
	v_mov_b32_e32 v93, v0
	v_mov_b32_e32 v94, v0
	v_mov_b32_e32 v95, v0
	v_mov_b32_e32 v104, v0
	v_mov_b32_e32 v105, v0
	v_mov_b32_e32 v106, v0
	v_mov_b32_e32 v107, v0
	v_mov_b32_e32 v112, v0
	v_mov_b32_e32 v113, v0
	v_mov_b32_e32 v114, v0
	v_mov_b32_e32 v115, v0
	v_mov_b32_e32 v120, v0
	v_mov_b32_e32 v121, v0
	v_mov_b32_e32 v122, v0
	v_mov_b32_e32 v123, v0
	v_mov_b32_e32 v124, v0
	v_mov_b32_e32 v125, v0
	v_mov_b32_e32 v126, v0
	v_mov_b32_e32 v127, v0
	.p2align	6

.LBB0_1170:
	s_ashr_i32 s35, s34, 31
	s_lshl_b64 s[38:39], s[34:35], 19
	s_add_u32 s38, s60, s38
	s_addc_u32 s39, s61, s39
	s_and_b64 s[40:41], s[8:9], exec
	s_cselect_b32 s35, s39, s49
	s_cselect_b32 s43, s38, s48
	s_ashr_i32 s37, s36, 31
	s_lshl_b64 s[40:41], s[36:37], 19
	s_add_u32 s40, s62, s40
	s_addc_u32 s41, s63, s41
	s_and_b64 s[50:51], s[8:9], exec
	s_cselect_b32 s37, s41, s47
	s_cselect_b32 s45, s40, s46
	s_add_u32 s52, s46, 0x10000
	s_addc_u32 s53, s47, 0
	s_add_u32 s46, s48, 0x40080
	v_mov_b32_e32 v0, 0
	s_addc_u32 s47, s49, 0
	s_mov_b32 s54, -2
	v_mov_b32_e32 v1, v0
	v_mov_b32_e32 v2, v0
	v_mov_b32_e32 v3, v0
	v_mov_b32_e32 v4, v0
	v_mov_b32_e32 v5, v0
	v_mov_b32_e32 v6, v0
	v_mov_b32_e32 v7, v0
	v_mov_b32_e32 v8, v0
	v_mov_b32_e32 v9, v0
	v_mov_b32_e32 v10, v0
	v_mov_b32_e32 v11, v0
	v_mov_b32_e32 v16, v0
	v_mov_b32_e32 v17, v0
	v_mov_b32_e32 v18, v0
	v_mov_b32_e32 v19, v0
	v_mov_b32_e32 v32, v0
	v_mov_b32_e32 v33, v0
	v_mov_b32_e32 v34, v0
	v_mov_b32_e32 v35, v0
	v_mov_b32_e32 v36, v0
	v_mov_b32_e32 v37, v0
	v_mov_b32_e32 v38, v0
	v_mov_b32_e32 v39, v0
	v_mov_b32_e32 v40, v0
	v_mov_b32_e32 v41, v0
	v_mov_b32_e32 v42, v0
	v_mov_b32_e32 v43, v0
	v_mov_b32_e32 v44, v0
	v_mov_b32_e32 v45, v0
	v_mov_b32_e32 v46, v0
	v_mov_b32_e32 v47, v0
	v_mov_b32_e32 v12, v0
	v_mov_b32_e32 v13, v0
	v_mov_b32_e32 v14, v0
	v_mov_b32_e32 v15, v0
	v_mov_b32_e32 v20, v0
	v_mov_b32_e32 v21, v0
	v_mov_b32_e32 v22, v0
	v_mov_b32_e32 v23, v0
	v_mov_b32_e32 v24, v0
	v_mov_b32_e32 v25, v0
	v_mov_b32_e32 v26, v0
	v_mov_b32_e32 v27, v0
	v_mov_b32_e32 v28, v0
	v_mov_b32_e32 v29, v0
	v_mov_b32_e32 v30, v0
	v_mov_b32_e32 v31, v0
	v_mov_b32_e32 v48, v0
	v_mov_b32_e32 v49, v0
	v_mov_b32_e32 v50, v0
	v_mov_b32_e32 v51, v0
	v_mov_b32_e32 v52, v0
	v_mov_b32_e32 v53, v0
	v_mov_b32_e32 v54, v0
	v_mov_b32_e32 v55, v0
	v_mov_b32_e32 v56, v0
	v_mov_b32_e32 v57, v0
	v_mov_b32_e32 v58, v0
	v_mov_b32_e32 v59, v0
	v_mov_b32_e32 v60, v0
	v_mov_b32_e32 v61, v0
	v_mov_b32_e32 v62, v0
	v_mov_b32_e32 v63, v0
	v_mov_b32_e32 v64, v0
	v_mov_b32_e32 v65, v0
	v_mov_b32_e32 v66, v0
	v_mov_b32_e32 v67, v0
	v_mov_b32_e32 v68, v0
	v_mov_b32_e32 v69, v0
	v_mov_b32_e32 v70, v0
	v_mov_b32_e32 v71, v0
	v_mov_b32_e32 v72, v0
	v_mov_b32_e32 v73, v0
	v_mov_b32_e32 v74, v0
	v_mov_b32_e32 v75, v0
	v_mov_b32_e32 v76, v0
	v_mov_b32_e32 v77, v0
	v_mov_b32_e32 v78, v0
	v_mov_b32_e32 v79, v0
	v_mov_b32_e32 v96, v0
	v_mov_b32_e32 v97, v0
	v_mov_b32_e32 v98, v0
	v_mov_b32_e32 v99, v0
	v_mov_b32_e32 v100, v0
	v_mov_b32_e32 v101, v0
	v_mov_b32_e32 v102, v0
	v_mov_b32_e32 v103, v0
	v_mov_b32_e32 v104, v0
	v_mov_b32_e32 v105, v0
	v_mov_b32_e32 v106, v0
	v_mov_b32_e32 v107, v0
	v_mov_b32_e32 v108, v0
	v_mov_b32_e32 v109, v0
	v_mov_b32_e32 v110, v0
	v_mov_b32_e32 v111, v0
	v_mov_b32_e32 v80, v0
	v_mov_b32_e32 v81, v0
	v_mov_b32_e32 v82, v0
	v_mov_b32_e32 v83, v0
	v_mov_b32_e32 v84, v0
	v_mov_b32_e32 v85, v0
	v_mov_b32_e32 v86, v0
	v_mov_b32_e32 v87, v0
	v_mov_b32_e32 v88, v0
	v_mov_b32_e32 v89, v0
	v_mov_b32_e32 v90, v0
	v_mov_b32_e32 v91, v0
	v_mov_b32_e32 v92, v0
	v_mov_b32_e32 v93, v0
	v_mov_b32_e32 v94, v0
	v_mov_b32_e32 v95, v0
	v_mov_b32_e32 v112, v0
	v_mov_b32_e32 v113, v0
	v_mov_b32_e32 v114, v0
	v_mov_b32_e32 v115, v0
	v_mov_b32_e32 v116, v0
	v_mov_b32_e32 v117, v0
	v_mov_b32_e32 v118, v0
	v_mov_b32_e32 v119, v0
	v_mov_b32_e32 v120, v0
	v_mov_b32_e32 v121, v0
	v_mov_b32_e32 v122, v0
	v_mov_b32_e32 v123, v0
	v_mov_b32_e32 v124, v0
	v_mov_b32_e32 v125, v0
	v_mov_b32_e32 v126, v0
	v_mov_b32_e32 v127, v0
	.p2align	6

.LBB0_1252:
	s_ashr_i32 s11, s10, 31
	s_lshl_b64 s[16:17], s[10:11], 19
	s_add_u32 s16, s30, s16
	s_addc_u32 s17, s31, s17
	s_and_b64 s[18:19], s[0:1], exec
	s_cselect_b32 s11, s17, s27
	s_cselect_b32 s50, s16, s26
	s_ashr_i32 s13, s12, 31
	s_lshl_b64 s[18:19], s[12:13], 19
	s_add_u32 s18, s33, s18
	s_addc_u32 s19, s34, s19
	s_and_b64 s[28:29], s[0:1], exec
	s_cselect_b32 s13, s19, s25
	s_cselect_b32 s51, s18, s24
	s_add_u32 s52, s24, 0x10000
	s_addc_u32 s53, s25, 0
	s_add_u32 s24, s26, 0x40080
	v_mov_b32_e32 v0, 0
	s_addc_u32 s25, s27, 0
	s_mov_b32 s54, -2
	v_mov_b32_e32 v1, v0
	v_mov_b32_e32 v2, v0
	v_mov_b32_e32 v3, v0
	v_mov_b32_e32 v8, v0
	v_mov_b32_e32 v9, v0
	v_mov_b32_e32 v10, v0
	v_mov_b32_e32 v11, v0
	v_mov_b32_e32 v16, v0
	v_mov_b32_e32 v17, v0
	v_mov_b32_e32 v18, v0
	v_mov_b32_e32 v19, v0
	v_mov_b32_e32 v24, v0
	v_mov_b32_e32 v25, v0
	v_mov_b32_e32 v26, v0
	v_mov_b32_e32 v27, v0
	v_mov_b32_e32 v32, v0
	v_mov_b32_e32 v33, v0
	v_mov_b32_e32 v34, v0
	v_mov_b32_e32 v35, v0
	v_mov_b32_e32 v40, v0
	v_mov_b32_e32 v41, v0
	v_mov_b32_e32 v42, v0
	v_mov_b32_e32 v43, v0
	v_mov_b32_e32 v48, v0
	v_mov_b32_e32 v49, v0
	v_mov_b32_e32 v50, v0
	v_mov_b32_e32 v51, v0
	v_mov_b32_e32 v56, v0
	v_mov_b32_e32 v57, v0
	v_mov_b32_e32 v58, v0
	v_mov_b32_e32 v59, v0
	v_mov_b32_e32 v4, v0
	v_mov_b32_e32 v5, v0
	v_mov_b32_e32 v6, v0
	v_mov_b32_e32 v7, v0
	v_mov_b32_e32 v12, v0
	v_mov_b32_e32 v13, v0
	v_mov_b32_e32 v14, v0
	v_mov_b32_e32 v15, v0
	v_mov_b32_e32 v20, v0
	v_mov_b32_e32 v21, v0
	v_mov_b32_e32 v22, v0
	v_mov_b32_e32 v23, v0
	v_mov_b32_e32 v28, v0
	v_mov_b32_e32 v29, v0
	v_mov_b32_e32 v30, v0
	v_mov_b32_e32 v31, v0
	v_mov_b32_e32 v36, v0
	v_mov_b32_e32 v37, v0
	v_mov_b32_e32 v38, v0
	v_mov_b32_e32 v39, v0
	v_mov_b32_e32 v44, v0
	v_mov_b32_e32 v45, v0
	v_mov_b32_e32 v46, v0
	v_mov_b32_e32 v47, v0
	v_mov_b32_e32 v52, v0
	v_mov_b32_e32 v53, v0
	v_mov_b32_e32 v54, v0
	v_mov_b32_e32 v55, v0
	v_mov_b32_e32 v60, v0
	v_mov_b32_e32 v61, v0
	v_mov_b32_e32 v62, v0
	v_mov_b32_e32 v63, v0
	v_mov_b32_e32 v64, v0
	v_mov_b32_e32 v65, v0
	v_mov_b32_e32 v66, v0
	v_mov_b32_e32 v67, v0
	v_mov_b32_e32 v72, v0
	v_mov_b32_e32 v73, v0
	v_mov_b32_e32 v74, v0
	v_mov_b32_e32 v75, v0
	v_mov_b32_e32 v80, v0
	v_mov_b32_e32 v81, v0
	v_mov_b32_e32 v82, v0
	v_mov_b32_e32 v83, v0
	v_mov_b32_e32 v88, v0
	v_mov_b32_e32 v89, v0
	v_mov_b32_e32 v90, v0
	v_mov_b32_e32 v91, v0
	v_mov_b32_e32 v96, v0
	v_mov_b32_e32 v97, v0
	v_mov_b32_e32 v98, v0
	v_mov_b32_e32 v99, v0
	v_mov_b32_e32 v104, v0
	v_mov_b32_e32 v105, v0
	v_mov_b32_e32 v106, v0
	v_mov_b32_e32 v107, v0
	v_mov_b32_e32 v112, v0
	v_mov_b32_e32 v113, v0
	v_mov_b32_e32 v114, v0
	v_mov_b32_e32 v115, v0
	v_mov_b32_e32 v120, v0
	v_mov_b32_e32 v121, v0
	v_mov_b32_e32 v122, v0
	v_mov_b32_e32 v123, v0
	v_mov_b32_e32 v68, v0
	v_mov_b32_e32 v69, v0
	v_mov_b32_e32 v70, v0
	v_mov_b32_e32 v71, v0
	v_mov_b32_e32 v76, v0
	v_mov_b32_e32 v77, v0
	v_mov_b32_e32 v78, v0
	v_mov_b32_e32 v79, v0
	v_mov_b32_e32 v84, v0
	v_mov_b32_e32 v85, v0
	v_mov_b32_e32 v86, v0
	v_mov_b32_e32 v87, v0
	v_mov_b32_e32 v92, v0
	v_mov_b32_e32 v93, v0
	v_mov_b32_e32 v94, v0
	v_mov_b32_e32 v95, v0
	v_mov_b32_e32 v100, v0
	v_mov_b32_e32 v101, v0
	v_mov_b32_e32 v102, v0
	v_mov_b32_e32 v103, v0
	v_mov_b32_e32 v108, v0
	v_mov_b32_e32 v109, v0
	v_mov_b32_e32 v110, v0
	v_mov_b32_e32 v111, v0
	v_mov_b32_e32 v116, v0
	v_mov_b32_e32 v117, v0
	v_mov_b32_e32 v118, v0
	v_mov_b32_e32 v119, v0
	v_mov_b32_e32 v124, v0
	v_mov_b32_e32 v125, v0
	v_mov_b32_e32 v126, v0
	v_mov_b32_e32 v127, v0
	.p2align	6

.LBB0_1480:
	s_add_u32 s68, s36, 0x10000
	s_addc_u32 s69, s37, 0
	s_add_u32 s36, s38, 0xc000
	v_mov_b32_e32 v0, 0
	s_addc_u32 s37, s39, 0
	s_mov_b32 s70, -2
	v_mov_b32_e32 v1, v0
	v_mov_b32_e32 v2, v0
	v_mov_b32_e32 v3, v0
	v_mov_b32_e32 v4, v0
	v_mov_b32_e32 v5, v0
	v_mov_b32_e32 v6, v0
	v_mov_b32_e32 v7, v0
	v_mov_b32_e32 v8, v0
	v_mov_b32_e32 v9, v0
	v_mov_b32_e32 v10, v0
	v_mov_b32_e32 v11, v0
	v_mov_b32_e32 v16, v0
	v_mov_b32_e32 v17, v0
	v_mov_b32_e32 v18, v0
	v_mov_b32_e32 v19, v0
	v_mov_b32_e32 v32, v0
	v_mov_b32_e32 v33, v0
	v_mov_b32_e32 v34, v0
	v_mov_b32_e32 v35, v0
	v_mov_b32_e32 v36, v0
	v_mov_b32_e32 v37, v0
	v_mov_b32_e32 v38, v0
	v_mov_b32_e32 v39, v0
	v_mov_b32_e32 v40, v0
	v_mov_b32_e32 v41, v0
	v_mov_b32_e32 v42, v0
	v_mov_b32_e32 v43, v0
	v_mov_b32_e32 v44, v0
	v_mov_b32_e32 v45, v0
	v_mov_b32_e32 v46, v0
	v_mov_b32_e32 v47, v0
	v_mov_b32_e32 v12, v0
	v_mov_b32_e32 v13, v0
	v_mov_b32_e32 v14, v0
	v_mov_b32_e32 v15, v0
	v_mov_b32_e32 v20, v0
	v_mov_b32_e32 v21, v0
	v_mov_b32_e32 v22, v0
	v_mov_b32_e32 v23, v0
	v_mov_b32_e32 v24, v0
	v_mov_b32_e32 v25, v0
	v_mov_b32_e32 v26, v0
	v_mov_b32_e32 v27, v0
	v_mov_b32_e32 v28, v0
	v_mov_b32_e32 v29, v0
	v_mov_b32_e32 v30, v0
	v_mov_b32_e32 v31, v0
	v_mov_b32_e32 v48, v0
	v_mov_b32_e32 v49, v0
	v_mov_b32_e32 v50, v0
	v_mov_b32_e32 v51, v0
	v_mov_b32_e32 v52, v0
	v_mov_b32_e32 v53, v0
	v_mov_b32_e32 v54, v0
	v_mov_b32_e32 v55, v0
	v_mov_b32_e32 v56, v0
	v_mov_b32_e32 v57, v0
	v_mov_b32_e32 v58, v0
	v_mov_b32_e32 v59, v0
	v_mov_b32_e32 v60, v0
	v_mov_b32_e32 v61, v0
	v_mov_b32_e32 v62, v0
	v_mov_b32_e32 v63, v0
	v_mov_b32_e32 v64, v0
	v_mov_b32_e32 v65, v0
	v_mov_b32_e32 v66, v0
	v_mov_b32_e32 v67, v0
	v_mov_b32_e32 v68, v0
	v_mov_b32_e32 v69, v0
	v_mov_b32_e32 v70, v0
	v_mov_b32_e32 v71, v0
	v_mov_b32_e32 v72, v0
	v_mov_b32_e32 v73, v0
	v_mov_b32_e32 v74, v0
	v_mov_b32_e32 v75, v0
	v_mov_b32_e32 v76, v0
	v_mov_b32_e32 v77, v0
	v_mov_b32_e32 v78, v0
	v_mov_b32_e32 v79, v0
	v_mov_b32_e32 v96, v0
	v_mov_b32_e32 v97, v0
	v_mov_b32_e32 v98, v0
	v_mov_b32_e32 v99, v0
	v_mov_b32_e32 v100, v0
	v_mov_b32_e32 v101, v0
	v_mov_b32_e32 v102, v0
	v_mov_b32_e32 v103, v0
	v_mov_b32_e32 v104, v0
	v_mov_b32_e32 v105, v0
	v_mov_b32_e32 v106, v0
	v_mov_b32_e32 v107, v0
	v_mov_b32_e32 v108, v0
	v_mov_b32_e32 v109, v0
	v_mov_b32_e32 v110, v0
	v_mov_b32_e32 v111, v0
	v_mov_b32_e32 v80, v0
	v_mov_b32_e32 v81, v0
	v_mov_b32_e32 v82, v0
	v_mov_b32_e32 v83, v0
	v_mov_b32_e32 v84, v0
	v_mov_b32_e32 v85, v0
	v_mov_b32_e32 v86, v0
	v_mov_b32_e32 v87, v0
	v_mov_b32_e32 v88, v0
	v_mov_b32_e32 v89, v0
	v_mov_b32_e32 v90, v0
	v_mov_b32_e32 v91, v0
	v_mov_b32_e32 v92, v0
	v_mov_b32_e32 v93, v0
	v_mov_b32_e32 v94, v0
	v_mov_b32_e32 v95, v0
	v_mov_b32_e32 v112, v0
	v_mov_b32_e32 v113, v0
	v_mov_b32_e32 v114, v0
	v_mov_b32_e32 v115, v0
	v_mov_b32_e32 v116, v0
	v_mov_b32_e32 v117, v0
	v_mov_b32_e32 v118, v0
	v_mov_b32_e32 v119, v0
	v_mov_b32_e32 v120, v0
	v_mov_b32_e32 v121, v0
	v_mov_b32_e32 v122, v0
	v_mov_b32_e32 v123, v0
	v_mov_b32_e32 v124, v0
	v_mov_b32_e32 v125, v0
	v_mov_b32_e32 v126, v0
	v_mov_b32_e32 v127, v0
	.p2align	6

.LBB0_1562:
	s_ashr_i32 s9, s8, 31
	s_lshl_b64 s[12:13], s[8:9], 19
	s_add_u32 s12, s28, s12
	s_addc_u32 s13, s29, s13
	s_cmp_eq_u32 s53, 2
	s_cselect_b32 s55, 0x40000, 0
	s_add_u32 s12, s12, s55
	s_addc_u32 s13, s13, 0
	s_and_b64 s[14:15], s[0:1], exec
	s_cselect_b32 s9, s13, s23
	s_cselect_b32 s45, s12, s22
	s_ashr_i32 s11, s10, 31
	s_lshl_b64 s[14:15], s[10:11], 19
	s_add_u32 s14, s30, s14
	s_addc_u32 s15, s31, s15
	s_and_b64 s[24:25], s[0:1], exec
	s_cselect_b32 s11, s15, s21
	s_cselect_b32 s46, s14, s20
	s_add_u32 s47, s20, 0x10000
	s_addc_u32 s48, s21, 0
	s_add_u32 s20, s22, 0x40080
	v_mov_b32_e32 v0, 0
	s_addc_u32 s21, s23, 0
	s_mov_b32 s49, -2
	v_mov_b32_e32 v1, v0
	v_mov_b32_e32 v2, v0
	v_mov_b32_e32 v3, v0
	v_mov_b32_e32 v8, v0
	v_mov_b32_e32 v9, v0
	v_mov_b32_e32 v10, v0
	v_mov_b32_e32 v11, v0
	v_mov_b32_e32 v16, v0
	v_mov_b32_e32 v17, v0
	v_mov_b32_e32 v18, v0
	v_mov_b32_e32 v19, v0
	v_mov_b32_e32 v24, v0
	v_mov_b32_e32 v25, v0
	v_mov_b32_e32 v26, v0
	v_mov_b32_e32 v27, v0
	v_mov_b32_e32 v32, v0
	v_mov_b32_e32 v33, v0
	v_mov_b32_e32 v34, v0
	v_mov_b32_e32 v35, v0
	v_mov_b32_e32 v40, v0
	v_mov_b32_e32 v41, v0
	v_mov_b32_e32 v42, v0
	v_mov_b32_e32 v43, v0
	v_mov_b32_e32 v48, v0
	v_mov_b32_e32 v49, v0
	v_mov_b32_e32 v50, v0
	v_mov_b32_e32 v51, v0
	v_mov_b32_e32 v56, v0
	v_mov_b32_e32 v57, v0
	v_mov_b32_e32 v58, v0
	v_mov_b32_e32 v59, v0
	v_mov_b32_e32 v4, v0
	v_mov_b32_e32 v5, v0
	v_mov_b32_e32 v6, v0
	v_mov_b32_e32 v7, v0
	v_mov_b32_e32 v12, v0
	v_mov_b32_e32 v13, v0
	v_mov_b32_e32 v14, v0
	v_mov_b32_e32 v15, v0
	v_mov_b32_e32 v20, v0
	v_mov_b32_e32 v21, v0
	v_mov_b32_e32 v22, v0
	v_mov_b32_e32 v23, v0
	v_mov_b32_e32 v28, v0
	v_mov_b32_e32 v29, v0
	v_mov_b32_e32 v30, v0
	v_mov_b32_e32 v31, v0
	v_mov_b32_e32 v36, v0
	v_mov_b32_e32 v37, v0
	v_mov_b32_e32 v38, v0
	v_mov_b32_e32 v39, v0
	v_mov_b32_e32 v44, v0
	v_mov_b32_e32 v45, v0
	v_mov_b32_e32 v46, v0
	v_mov_b32_e32 v47, v0
	v_mov_b32_e32 v52, v0
	v_mov_b32_e32 v53, v0
	v_mov_b32_e32 v54, v0
	v_mov_b32_e32 v55, v0
	v_mov_b32_e32 v60, v0
	v_mov_b32_e32 v61, v0
	v_mov_b32_e32 v62, v0
	v_mov_b32_e32 v63, v0
	v_mov_b32_e32 v64, v0
	v_mov_b32_e32 v65, v0
	v_mov_b32_e32 v66, v0
	v_mov_b32_e32 v67, v0
	v_mov_b32_e32 v72, v0
	v_mov_b32_e32 v73, v0
	v_mov_b32_e32 v74, v0
	v_mov_b32_e32 v75, v0
	v_mov_b32_e32 v80, v0
	v_mov_b32_e32 v81, v0
	v_mov_b32_e32 v82, v0
	v_mov_b32_e32 v83, v0
	v_mov_b32_e32 v88, v0
	v_mov_b32_e32 v89, v0
	v_mov_b32_e32 v90, v0
	v_mov_b32_e32 v91, v0
	v_mov_b32_e32 v96, v0
	v_mov_b32_e32 v97, v0
	v_mov_b32_e32 v98, v0
	v_mov_b32_e32 v99, v0
	v_mov_b32_e32 v104, v0
	v_mov_b32_e32 v105, v0
	v_mov_b32_e32 v106, v0
	v_mov_b32_e32 v107, v0
	v_mov_b32_e32 v112, v0
	v_mov_b32_e32 v113, v0
	v_mov_b32_e32 v114, v0
	v_mov_b32_e32 v115, v0
	v_mov_b32_e32 v120, v0
	v_mov_b32_e32 v121, v0
	v_mov_b32_e32 v122, v0
	v_mov_b32_e32 v123, v0
	v_mov_b32_e32 v68, v0
	v_mov_b32_e32 v69, v0
	v_mov_b32_e32 v70, v0
	v_mov_b32_e32 v71, v0
	v_mov_b32_e32 v76, v0
	v_mov_b32_e32 v77, v0
	v_mov_b32_e32 v78, v0
	v_mov_b32_e32 v79, v0
	v_mov_b32_e32 v84, v0
	v_mov_b32_e32 v85, v0
	v_mov_b32_e32 v86, v0
	v_mov_b32_e32 v87, v0
	v_mov_b32_e32 v92, v0
	v_mov_b32_e32 v93, v0
	v_mov_b32_e32 v94, v0
	v_mov_b32_e32 v95, v0
	v_mov_b32_e32 v100, v0
	v_mov_b32_e32 v101, v0
	v_mov_b32_e32 v102, v0
	v_mov_b32_e32 v103, v0
	v_mov_b32_e32 v108, v0
	v_mov_b32_e32 v109, v0
	v_mov_b32_e32 v110, v0
	v_mov_b32_e32 v111, v0
	v_mov_b32_e32 v116, v0
	v_mov_b32_e32 v117, v0
	v_mov_b32_e32 v118, v0
	v_mov_b32_e32 v119, v0
	v_mov_b32_e32 v124, v0
	v_mov_b32_e32 v125, v0
	v_mov_b32_e32 v126, v0
	v_mov_b32_e32 v127, v0
	.p2align	6

.LBB0_1644:
	s_add_u32 s45, s36, 0x10000
	s_addc_u32 s46, s37, 0
	s_add_u32 s36, s38, 0xc000
	v_mov_b32_e32 v0, 0
	s_addc_u32 s37, s39, 0
	s_mov_b32 s47, -2
	v_mov_b32_e32 v1, v0
	v_mov_b32_e32 v2, v0
	v_mov_b32_e32 v3, v0
	v_mov_b32_e32 v4, v0
	v_mov_b32_e32 v5, v0
	v_mov_b32_e32 v6, v0
	v_mov_b32_e32 v7, v0
	v_mov_b32_e32 v8, v0
	v_mov_b32_e32 v9, v0
	v_mov_b32_e32 v10, v0
	v_mov_b32_e32 v11, v0
	v_mov_b32_e32 v16, v0
	v_mov_b32_e32 v17, v0
	v_mov_b32_e32 v18, v0
	v_mov_b32_e32 v19, v0
	v_mov_b32_e32 v32, v0
	v_mov_b32_e32 v33, v0
	v_mov_b32_e32 v34, v0
	v_mov_b32_e32 v35, v0
	v_mov_b32_e32 v36, v0
	v_mov_b32_e32 v37, v0
	v_mov_b32_e32 v38, v0
	v_mov_b32_e32 v39, v0
	v_mov_b32_e32 v40, v0
	v_mov_b32_e32 v41, v0
	v_mov_b32_e32 v42, v0
	v_mov_b32_e32 v43, v0
	v_mov_b32_e32 v44, v0
	v_mov_b32_e32 v45, v0
	v_mov_b32_e32 v46, v0
	v_mov_b32_e32 v47, v0
	v_mov_b32_e32 v12, v0
	v_mov_b32_e32 v13, v0
	v_mov_b32_e32 v14, v0
	v_mov_b32_e32 v15, v0
	v_mov_b32_e32 v20, v0
	v_mov_b32_e32 v21, v0
	v_mov_b32_e32 v22, v0
	v_mov_b32_e32 v23, v0
	v_mov_b32_e32 v24, v0
	v_mov_b32_e32 v25, v0
	v_mov_b32_e32 v26, v0
	v_mov_b32_e32 v27, v0
	v_mov_b32_e32 v28, v0
	v_mov_b32_e32 v29, v0
	v_mov_b32_e32 v30, v0
	v_mov_b32_e32 v31, v0
	v_mov_b32_e32 v48, v0
	v_mov_b32_e32 v49, v0
	v_mov_b32_e32 v50, v0
	v_mov_b32_e32 v51, v0
	v_mov_b32_e32 v52, v0
	v_mov_b32_e32 v53, v0
	v_mov_b32_e32 v54, v0
	v_mov_b32_e32 v55, v0
	v_mov_b32_e32 v56, v0
	v_mov_b32_e32 v57, v0
	v_mov_b32_e32 v58, v0
	v_mov_b32_e32 v59, v0
	v_mov_b32_e32 v60, v0
	v_mov_b32_e32 v61, v0
	v_mov_b32_e32 v62, v0
	v_mov_b32_e32 v63, v0
	v_mov_b32_e32 v64, v0
	v_mov_b32_e32 v65, v0
	v_mov_b32_e32 v66, v0
	v_mov_b32_e32 v67, v0
	v_mov_b32_e32 v68, v0
	v_mov_b32_e32 v69, v0
	v_mov_b32_e32 v70, v0
	v_mov_b32_e32 v71, v0
	v_mov_b32_e32 v72, v0
	v_mov_b32_e32 v73, v0
	v_mov_b32_e32 v74, v0
	v_mov_b32_e32 v75, v0
	v_mov_b32_e32 v76, v0
	v_mov_b32_e32 v77, v0
	v_mov_b32_e32 v78, v0
	v_mov_b32_e32 v79, v0
	v_mov_b32_e32 v96, v0
	v_mov_b32_e32 v97, v0
	v_mov_b32_e32 v98, v0
	v_mov_b32_e32 v99, v0
	v_mov_b32_e32 v100, v0
	v_mov_b32_e32 v101, v0
	v_mov_b32_e32 v102, v0
	v_mov_b32_e32 v103, v0
	v_mov_b32_e32 v104, v0
	v_mov_b32_e32 v105, v0
	v_mov_b32_e32 v106, v0
	v_mov_b32_e32 v107, v0
	v_mov_b32_e32 v108, v0
	v_mov_b32_e32 v109, v0
	v_mov_b32_e32 v110, v0
	v_mov_b32_e32 v111, v0
	v_mov_b32_e32 v80, v0
	v_mov_b32_e32 v81, v0
	v_mov_b32_e32 v82, v0
	v_mov_b32_e32 v83, v0
	v_mov_b32_e32 v84, v0
	v_mov_b32_e32 v85, v0
	v_mov_b32_e32 v86, v0
	v_mov_b32_e32 v87, v0
	v_mov_b32_e32 v88, v0
	v_mov_b32_e32 v89, v0
	v_mov_b32_e32 v90, v0
	v_mov_b32_e32 v91, v0
	v_mov_b32_e32 v92, v0
	v_mov_b32_e32 v93, v0
	v_mov_b32_e32 v94, v0
	v_mov_b32_e32 v95, v0
	v_mov_b32_e32 v112, v0
	v_mov_b32_e32 v113, v0
	v_mov_b32_e32 v114, v0
	v_mov_b32_e32 v115, v0
	v_mov_b32_e32 v116, v0
	v_mov_b32_e32 v117, v0
	v_mov_b32_e32 v118, v0
	v_mov_b32_e32 v119, v0
	v_mov_b32_e32 v120, v0
	v_mov_b32_e32 v121, v0
	v_mov_b32_e32 v122, v0
	v_mov_b32_e32 v123, v0
	v_mov_b32_e32 v124, v0
	v_mov_b32_e32 v125, v0
	v_mov_b32_e32 v126, v0
	v_mov_b32_e32 v127, v0
	.p2align	6

.LBB0_1728:
	s_ashr_i32 s19, s18, 31
	s_lshl_b64 s[22:23], s[18:19], 19
	s_add_u32 s22, s37, s22
	s_addc_u32 s23, s38, s23
	s_and_b64 s[24:25], s[4:5], exec
	s_cselect_b32 s1, s23, s27
	s_cselect_b32 s19, s22, s26
	s_ashr_i32 s21, s20, 31
	s_lshl_b64 s[24:25], s[20:21], 19
	s_add_u32 s24, s39, s24
	s_addc_u32 s25, s40, s25
	s_and_b64 s[28:29], s[4:5], exec
	s_cselect_b32 s21, s25, s7
	s_cselect_b32 s30, s24, s6
	s_add_u32 s31, s6, 0x10000
	s_addc_u32 s34, s7, 0
	s_add_u32 s6, s26, 0x40080
	v_mov_b32_e32 v0, 0
	s_addc_u32 s7, s27, 0
	s_mov_b32 s35, -2
	v_mov_b32_e32 v1, v0
	v_mov_b32_e32 v2, v0
	v_mov_b32_e32 v3, v0
	v_mov_b32_e32 v4, v0
	v_mov_b32_e32 v5, v0
	v_mov_b32_e32 v6, v0
	v_mov_b32_e32 v7, v0
	v_mov_b32_e32 v8, v0
	v_mov_b32_e32 v9, v0
	v_mov_b32_e32 v10, v0
	v_mov_b32_e32 v11, v0
	v_mov_b32_e32 v12, v0
	v_mov_b32_e32 v13, v0
	v_mov_b32_e32 v14, v0
	v_mov_b32_e32 v15, v0
	v_mov_b32_e32 v16, v0
	v_mov_b32_e32 v17, v0
	v_mov_b32_e32 v18, v0
	v_mov_b32_e32 v19, v0
	v_mov_b32_e32 v20, v0
	v_mov_b32_e32 v21, v0
	v_mov_b32_e32 v22, v0
	v_mov_b32_e32 v23, v0
	v_mov_b32_e32 v24, v0
	v_mov_b32_e32 v25, v0
	v_mov_b32_e32 v26, v0
	v_mov_b32_e32 v27, v0
	v_mov_b32_e32 v28, v0
	v_mov_b32_e32 v29, v0
	v_mov_b32_e32 v30, v0
	v_mov_b32_e32 v31, v0
	v_mov_b32_e32 v64, v0
	v_mov_b32_e32 v65, v0
	v_mov_b32_e32 v66, v0
	v_mov_b32_e32 v67, v0
	v_mov_b32_e32 v68, v0
	v_mov_b32_e32 v69, v0
	v_mov_b32_e32 v70, v0
	v_mov_b32_e32 v71, v0
	v_mov_b32_e32 v72, v0
	v_mov_b32_e32 v73, v0
	v_mov_b32_e32 v74, v0
	v_mov_b32_e32 v75, v0
	v_mov_b32_e32 v76, v0
	v_mov_b32_e32 v77, v0
	v_mov_b32_e32 v78, v0
	v_mov_b32_e32 v79, v0
	v_mov_b32_e32 v80, v0
	v_mov_b32_e32 v81, v0
	v_mov_b32_e32 v82, v0
	v_mov_b32_e32 v83, v0
	v_mov_b32_e32 v84, v0
	v_mov_b32_e32 v85, v0
	v_mov_b32_e32 v86, v0
	v_mov_b32_e32 v87, v0
	v_mov_b32_e32 v88, v0
	v_mov_b32_e32 v89, v0
	v_mov_b32_e32 v90, v0
	v_mov_b32_e32 v91, v0
	v_mov_b32_e32 v92, v0
	v_mov_b32_e32 v93, v0
	v_mov_b32_e32 v94, v0
	v_mov_b32_e32 v95, v0
	v_mov_b32_e32 v32, v0
	v_mov_b32_e32 v33, v0
	v_mov_b32_e32 v34, v0
	v_mov_b32_e32 v35, v0
	v_mov_b32_e32 v36, v0
	v_mov_b32_e32 v37, v0
	v_mov_b32_e32 v38, v0
	v_mov_b32_e32 v39, v0
	v_mov_b32_e32 v40, v0
	v_mov_b32_e32 v41, v0
	v_mov_b32_e32 v42, v0
	v_mov_b32_e32 v43, v0
	v_mov_b32_e32 v44, v0
	v_mov_b32_e32 v45, v0
	v_mov_b32_e32 v46, v0
	v_mov_b32_e32 v47, v0
	v_mov_b32_e32 v48, v0
	v_mov_b32_e32 v49, v0
	v_mov_b32_e32 v50, v0
	v_mov_b32_e32 v51, v0
	v_mov_b32_e32 v52, v0
	v_mov_b32_e32 v53, v0
	v_mov_b32_e32 v54, v0
	v_mov_b32_e32 v55, v0
	v_mov_b32_e32 v56, v0
	v_mov_b32_e32 v57, v0
	v_mov_b32_e32 v58, v0
	v_mov_b32_e32 v59, v0
	v_mov_b32_e32 v60, v0
	v_mov_b32_e32 v61, v0
	v_mov_b32_e32 v62, v0
	v_mov_b32_e32 v63, v0
	v_mov_b32_e32 v96, v0
	v_mov_b32_e32 v97, v0
	v_mov_b32_e32 v98, v0
	v_mov_b32_e32 v99, v0
	v_mov_b32_e32 v100, v0
	v_mov_b32_e32 v101, v0
	v_mov_b32_e32 v102, v0
	v_mov_b32_e32 v103, v0
	v_mov_b32_e32 v104, v0
	v_mov_b32_e32 v105, v0
	v_mov_b32_e32 v106, v0
	v_mov_b32_e32 v107, v0
	v_mov_b32_e32 v108, v0
	v_mov_b32_e32 v109, v0
	v_mov_b32_e32 v110, v0
	v_mov_b32_e32 v111, v0
	v_mov_b32_e32 v112, v0
	v_mov_b32_e32 v113, v0
	v_mov_b32_e32 v114, v0
	v_mov_b32_e32 v115, v0
	v_mov_b32_e32 v116, v0
	v_mov_b32_e32 v117, v0
	v_mov_b32_e32 v118, v0
	v_mov_b32_e32 v119, v0
	v_mov_b32_e32 v120, v0
	v_mov_b32_e32 v121, v0
	v_mov_b32_e32 v122, v0
	v_mov_b32_e32 v123, v0
	v_mov_b32_e32 v124, v0
	v_mov_b32_e32 v125, v0
	v_mov_b32_e32 v126, v0
	v_mov_b32_e32 v127, v0
	.p2align	6

.LBB0_2518:
	s_add_u32 s62, s30, 0x10000
	s_addc_u32 s63, s31, 0
	s_add_u32 s30, s34, 0xc000
	v_mov_b32_e32 v0, 0
	s_addc_u32 s31, s35, 0
	s_mov_b32 s64, -2
	v_mov_b32_e32 v1, v0
	v_mov_b32_e32 v2, v0
	v_mov_b32_e32 v3, v0
	v_mov_b32_e32 v4, v0
	v_mov_b32_e32 v5, v0
	v_mov_b32_e32 v6, v0
	v_mov_b32_e32 v7, v0
	v_mov_b32_e32 v8, v0
	v_mov_b32_e32 v9, v0
	v_mov_b32_e32 v10, v0
	v_mov_b32_e32 v11, v0
	v_mov_b32_e32 v16, v0
	v_mov_b32_e32 v17, v0
	v_mov_b32_e32 v18, v0
	v_mov_b32_e32 v19, v0
	v_mov_b32_e32 v32, v0
	v_mov_b32_e32 v33, v0
	v_mov_b32_e32 v34, v0
	v_mov_b32_e32 v35, v0
	v_mov_b32_e32 v36, v0
	v_mov_b32_e32 v37, v0
	v_mov_b32_e32 v38, v0
	v_mov_b32_e32 v39, v0
	v_mov_b32_e32 v40, v0
	v_mov_b32_e32 v41, v0
	v_mov_b32_e32 v42, v0
	v_mov_b32_e32 v43, v0
	v_mov_b32_e32 v44, v0
	v_mov_b32_e32 v45, v0
	v_mov_b32_e32 v46, v0
	v_mov_b32_e32 v47, v0
	v_mov_b32_e32 v12, v0
	v_mov_b32_e32 v13, v0
	v_mov_b32_e32 v14, v0
	v_mov_b32_e32 v15, v0
	v_mov_b32_e32 v20, v0
	v_mov_b32_e32 v21, v0
	v_mov_b32_e32 v22, v0
	v_mov_b32_e32 v23, v0
	v_mov_b32_e32 v24, v0
	v_mov_b32_e32 v25, v0
	v_mov_b32_e32 v26, v0
	v_mov_b32_e32 v27, v0
	v_mov_b32_e32 v28, v0
	v_mov_b32_e32 v29, v0
	v_mov_b32_e32 v30, v0
	v_mov_b32_e32 v31, v0
	v_mov_b32_e32 v48, v0
	v_mov_b32_e32 v49, v0
	v_mov_b32_e32 v50, v0
	v_mov_b32_e32 v51, v0
	v_mov_b32_e32 v52, v0
	v_mov_b32_e32 v53, v0
	v_mov_b32_e32 v54, v0
	v_mov_b32_e32 v55, v0
	v_mov_b32_e32 v56, v0
	v_mov_b32_e32 v57, v0
	v_mov_b32_e32 v58, v0
	v_mov_b32_e32 v59, v0
	v_mov_b32_e32 v60, v0
	v_mov_b32_e32 v61, v0
	v_mov_b32_e32 v62, v0
	v_mov_b32_e32 v63, v0
	v_mov_b32_e32 v64, v0
	v_mov_b32_e32 v65, v0
	v_mov_b32_e32 v66, v0
	v_mov_b32_e32 v67, v0
	v_mov_b32_e32 v68, v0
	v_mov_b32_e32 v69, v0
	v_mov_b32_e32 v70, v0
	v_mov_b32_e32 v71, v0
	v_mov_b32_e32 v72, v0
	v_mov_b32_e32 v73, v0
	v_mov_b32_e32 v74, v0
	v_mov_b32_e32 v75, v0
	v_mov_b32_e32 v76, v0
	v_mov_b32_e32 v77, v0
	v_mov_b32_e32 v78, v0
	v_mov_b32_e32 v79, v0
	v_mov_b32_e32 v96, v0
	v_mov_b32_e32 v97, v0
	v_mov_b32_e32 v98, v0
	v_mov_b32_e32 v99, v0
	v_mov_b32_e32 v100, v0
	v_mov_b32_e32 v101, v0
	v_mov_b32_e32 v102, v0
	v_mov_b32_e32 v103, v0
	v_mov_b32_e32 v104, v0
	v_mov_b32_e32 v105, v0
	v_mov_b32_e32 v106, v0
	v_mov_b32_e32 v107, v0
	v_mov_b32_e32 v108, v0
	v_mov_b32_e32 v109, v0
	v_mov_b32_e32 v110, v0
	v_mov_b32_e32 v111, v0
	v_mov_b32_e32 v80, v0
	v_mov_b32_e32 v81, v0
	v_mov_b32_e32 v82, v0
	v_mov_b32_e32 v83, v0
	v_mov_b32_e32 v84, v0
	v_mov_b32_e32 v85, v0
	v_mov_b32_e32 v86, v0
	v_mov_b32_e32 v87, v0
	v_mov_b32_e32 v88, v0
	v_mov_b32_e32 v89, v0
	v_mov_b32_e32 v90, v0
	v_mov_b32_e32 v91, v0
	v_mov_b32_e32 v92, v0
	v_mov_b32_e32 v93, v0
	v_mov_b32_e32 v94, v0
	v_mov_b32_e32 v95, v0
	v_mov_b32_e32 v112, v0
	v_mov_b32_e32 v113, v0
	v_mov_b32_e32 v114, v0
	v_mov_b32_e32 v115, v0
	v_mov_b32_e32 v116, v0
	v_mov_b32_e32 v117, v0
	v_mov_b32_e32 v118, v0
	v_mov_b32_e32 v119, v0
	v_mov_b32_e32 v120, v0
	v_mov_b32_e32 v121, v0
	v_mov_b32_e32 v122, v0
	v_mov_b32_e32 v123, v0
	v_mov_b32_e32 v124, v0
	v_mov_b32_e32 v125, v0
	v_mov_b32_e32 v126, v0
	v_mov_b32_e32 v127, v0
	.p2align	6
